# S5 phases: weight-transpose waves paced with s_sleep 64 per item (they have slack; less memory traffic beside the scan waves early in the phase)
# speedup vs baseline: 1.0157x; 1.0063x over previous
.LBB0_280:
	s_sleep 64
	s_add_i32 s1, s1, s73
	s_add_i32 s4, s4, s73
	s_add_i32 s5, s1, 0xffffd000
	s_cmpk_lt_i32 s5, 0x3000
	s_cbranch_scc0 .LBB0_319
